# prologue x->bf16 loop: 32 loads in flight per wave (8 rows), batched wave sums; mem-row gain loads hoisted
# baseline (speedup 1.0000x reference)
.Lxc_head:
	s_mul_i32 s16, s46, 7
	s_add_i32 s16, s16, s19
	s_cmpk_gt_i32 s16, 0x3fff
	s_cbranch_scc1 .LBB0_47
	s_add_u32 s50, s42, s18
	s_addc_u32 s51, s43, 0
	global_load_dwordx4 v[64:67], v[4:5], off offset:-3072
	global_load_dwordx4 v[68:71], v[4:5], off offset:-2048
	global_load_dwordx4 v[72:75], v[4:5], off offset:-1024
	global_load_dwordx4 v[76:79], v[4:5], off
	v_lshl_add_u64 v[4:5], v[4:5], 0, s[14:15]
	global_load_dwordx4 v[80:83], v[4:5], off offset:-3072
	global_load_dwordx4 v[84:87], v[4:5], off offset:-2048
	global_load_dwordx4 v[88:91], v[4:5], off offset:-1024
	global_load_dwordx4 v[92:95], v[4:5], off
	v_lshl_add_u64 v[4:5], v[4:5], 0, s[14:15]
	global_load_dwordx4 v[96:99], v[4:5], off offset:-3072
	global_load_dwordx4 v[100:103], v[4:5], off offset:-2048
	global_load_dwordx4 v[104:107], v[4:5], off offset:-1024
	global_load_dwordx4 v[108:111], v[4:5], off
	v_lshl_add_u64 v[4:5], v[4:5], 0, s[14:15]
	global_load_dwordx4 v[112:115], v[4:5], off offset:-3072
	global_load_dwordx4 v[116:119], v[4:5], off offset:-2048
	global_load_dwordx4 v[120:123], v[4:5], off offset:-1024
	global_load_dwordx4 v[124:127], v[4:5], off
	v_lshl_add_u64 v[4:5], v[4:5], 0, s[14:15]
	global_load_dwordx4 v[128:131], v[4:5], off offset:-3072
	global_load_dwordx4 v[132:135], v[4:5], off offset:-2048
	global_load_dwordx4 v[136:139], v[4:5], off offset:-1024
	global_load_dwordx4 v[140:143], v[4:5], off
	v_lshl_add_u64 v[4:5], v[4:5], 0, s[14:15]
	global_load_dwordx4 v[144:147], v[4:5], off offset:-3072
	global_load_dwordx4 v[148:151], v[4:5], off offset:-2048
	global_load_dwordx4 v[152:155], v[4:5], off offset:-1024
	global_load_dwordx4 v[156:159], v[4:5], off
	v_lshl_add_u64 v[4:5], v[4:5], 0, s[14:15]
	global_load_dwordx4 v[160:163], v[4:5], off offset:-3072
	global_load_dwordx4 v[164:167], v[4:5], off offset:-2048
	global_load_dwordx4 v[168:171], v[4:5], off offset:-1024
	global_load_dwordx4 v[172:175], v[4:5], off
	v_lshl_add_u64 v[4:5], v[4:5], 0, s[14:15]
	global_load_dwordx4 v[176:179], v[4:5], off offset:-3072
	global_load_dwordx4 v[180:183], v[4:5], off offset:-2048
	global_load_dwordx4 v[184:187], v[4:5], off offset:-1024
	global_load_dwordx4 v[188:191], v[4:5], off
	v_lshl_add_u64 v[4:5], v[4:5], 0, s[14:15]
	s_waitcnt vmcnt(28)
	v_mul_f32_e32 v12, v65, v65
	v_mul_f32_e32 v13, v67, v67
	v_fmac_f32_e32 v12, v64, v64
	v_fmac_f32_e32 v13, v66, v66
	v_add_f32_e32 v30, v12, v13
	v_mul_f32_e32 v12, v69, v69
	v_mul_f32_e32 v13, v71, v71
	v_fmac_f32_e32 v12, v68, v68
	v_fmac_f32_e32 v13, v70, v70
	v_add_f32_e32 v12, v12, v13
	v_add_f32_e32 v30, v30, v12
	v_mul_f32_e32 v12, v73, v73
	v_mul_f32_e32 v13, v75, v75
	v_fmac_f32_e32 v12, v72, v72
	v_fmac_f32_e32 v13, v74, v74
	v_add_f32_e32 v12, v12, v13
	v_add_f32_e32 v30, v30, v12
	v_mul_f32_e32 v12, v77, v77
	v_mul_f32_e32 v13, v79, v79
	v_fmac_f32_e32 v12, v76, v76
	v_fmac_f32_e32 v13, v78, v78
	v_add_f32_e32 v12, v12, v13
	v_add_f32_e32 v30, v30, v12
	v_cvt_pk_bf16_f32 v64, v64, v65
	v_cvt_pk_bf16_f32 v65, v66, v67
	v_cvt_pk_bf16_f32 v66, v68, v69
	v_cvt_pk_bf16_f32 v67, v70, v71
	v_cvt_pk_bf16_f32 v68, v72, v73
	v_cvt_pk_bf16_f32 v69, v74, v75
	v_cvt_pk_bf16_f32 v70, v76, v77
	v_cvt_pk_bf16_f32 v71, v78, v79
	v_lshl_add_u64 v[28:29], v[2:3], 0, s[50:51]
	global_store_dwordx2 v[28:29], v[64:65], off
	global_store_dwordx2 v[28:29], v[66:67], off offset:512
	global_store_dwordx2 v[28:29], v[68:69], off offset:1024
	global_store_dwordx2 v[28:29], v[70:71], off offset:1536
	v_lshl_add_u64 v[2:3], v[2:3], 0, s[12:13]
	s_waitcnt vmcnt(28)
	v_mul_f32_e32 v12, v81, v81
	v_mul_f32_e32 v13, v83, v83
	v_fmac_f32_e32 v12, v80, v80
	v_fmac_f32_e32 v13, v82, v82
	v_add_f32_e32 v31, v12, v13
	v_mul_f32_e32 v12, v85, v85
	v_mul_f32_e32 v13, v87, v87
	v_fmac_f32_e32 v12, v84, v84
	v_fmac_f32_e32 v13, v86, v86
	v_add_f32_e32 v12, v12, v13
	v_add_f32_e32 v31, v31, v12
	v_mul_f32_e32 v12, v89, v89
	v_mul_f32_e32 v13, v91, v91
	v_fmac_f32_e32 v12, v88, v88
	v_fmac_f32_e32 v13, v90, v90
	v_add_f32_e32 v12, v12, v13
	v_add_f32_e32 v31, v31, v12
	v_mul_f32_e32 v12, v93, v93
	v_mul_f32_e32 v13, v95, v95
	v_fmac_f32_e32 v12, v92, v92
	v_fmac_f32_e32 v13, v94, v94
	v_add_f32_e32 v12, v12, v13
	v_add_f32_e32 v31, v31, v12
	v_cvt_pk_bf16_f32 v80, v80, v81
	v_cvt_pk_bf16_f32 v81, v82, v83
	v_cvt_pk_bf16_f32 v82, v84, v85
	v_cvt_pk_bf16_f32 v83, v86, v87
	v_cvt_pk_bf16_f32 v84, v88, v89
	v_cvt_pk_bf16_f32 v85, v90, v91
	v_cvt_pk_bf16_f32 v86, v92, v93
	v_cvt_pk_bf16_f32 v87, v94, v95
	v_lshl_add_u64 v[28:29], v[2:3], 0, s[50:51]
	global_store_dwordx2 v[28:29], v[80:81], off
	global_store_dwordx2 v[28:29], v[82:83], off offset:512
	global_store_dwordx2 v[28:29], v[84:85], off offset:1024
	global_store_dwordx2 v[28:29], v[86:87], off offset:1536
	v_lshl_add_u64 v[2:3], v[2:3], 0, s[12:13]
	s_waitcnt vmcnt(28)
	v_mul_f32_e32 v12, v97, v97
	v_mul_f32_e32 v13, v99, v99
	v_fmac_f32_e32 v12, v96, v96
	v_fmac_f32_e32 v13, v98, v98
	v_add_f32_e32 v32, v12, v13
	v_mul_f32_e32 v12, v101, v101
	v_mul_f32_e32 v13, v103, v103
	v_fmac_f32_e32 v12, v100, v100
	v_fmac_f32_e32 v13, v102, v102
	v_add_f32_e32 v12, v12, v13
	v_add_f32_e32 v32, v32, v12
	v_mul_f32_e32 v12, v105, v105
	v_mul_f32_e32 v13, v107, v107
	v_fmac_f32_e32 v12, v104, v104
	v_fmac_f32_e32 v13, v106, v106
	v_add_f32_e32 v12, v12, v13
	v_add_f32_e32 v32, v32, v12
	v_mul_f32_e32 v12, v109, v109
	v_mul_f32_e32 v13, v111, v111
	v_fmac_f32_e32 v12, v108, v108
	v_fmac_f32_e32 v13, v110, v110
	v_add_f32_e32 v12, v12, v13
	v_add_f32_e32 v32, v32, v12
	v_cvt_pk_bf16_f32 v96, v96, v97
	v_cvt_pk_bf16_f32 v97, v98, v99
	v_cvt_pk_bf16_f32 v98, v100, v101
	v_cvt_pk_bf16_f32 v99, v102, v103
	v_cvt_pk_bf16_f32 v100, v104, v105
	v_cvt_pk_bf16_f32 v101, v106, v107
	v_cvt_pk_bf16_f32 v102, v108, v109
	v_cvt_pk_bf16_f32 v103, v110, v111
	v_lshl_add_u64 v[28:29], v[2:3], 0, s[50:51]
	global_store_dwordx2 v[28:29], v[96:97], off
	global_store_dwordx2 v[28:29], v[98:99], off offset:512
	global_store_dwordx2 v[28:29], v[100:101], off offset:1024
	global_store_dwordx2 v[28:29], v[102:103], off offset:1536
	v_lshl_add_u64 v[2:3], v[2:3], 0, s[12:13]
	s_waitcnt vmcnt(28)
	v_mul_f32_e32 v12, v113, v113
	v_mul_f32_e32 v13, v115, v115
	v_fmac_f32_e32 v12, v112, v112
	v_fmac_f32_e32 v13, v114, v114
	v_add_f32_e32 v33, v12, v13
	v_mul_f32_e32 v12, v117, v117
	v_mul_f32_e32 v13, v119, v119
	v_fmac_f32_e32 v12, v116, v116
	v_fmac_f32_e32 v13, v118, v118
	v_add_f32_e32 v12, v12, v13
	v_add_f32_e32 v33, v33, v12
	v_mul_f32_e32 v12, v121, v121
	v_mul_f32_e32 v13, v123, v123
	v_fmac_f32_e32 v12, v120, v120
	v_fmac_f32_e32 v13, v122, v122
	v_add_f32_e32 v12, v12, v13
	v_add_f32_e32 v33, v33, v12
	v_mul_f32_e32 v12, v125, v125
	v_mul_f32_e32 v13, v127, v127
	v_fmac_f32_e32 v12, v124, v124
	v_fmac_f32_e32 v13, v126, v126
	v_add_f32_e32 v12, v12, v13
	v_add_f32_e32 v33, v33, v12
	v_cvt_pk_bf16_f32 v112, v112, v113
	v_cvt_pk_bf16_f32 v113, v114, v115
	v_cvt_pk_bf16_f32 v114, v116, v117
	v_cvt_pk_bf16_f32 v115, v118, v119
	v_cvt_pk_bf16_f32 v116, v120, v121
	v_cvt_pk_bf16_f32 v117, v122, v123
	v_cvt_pk_bf16_f32 v118, v124, v125
	v_cvt_pk_bf16_f32 v119, v126, v127
	v_lshl_add_u64 v[28:29], v[2:3], 0, s[50:51]
	global_store_dwordx2 v[28:29], v[112:113], off
	global_store_dwordx2 v[28:29], v[114:115], off offset:512
	global_store_dwordx2 v[28:29], v[116:117], off offset:1024
	global_store_dwordx2 v[28:29], v[118:119], off offset:1536
	v_lshl_add_u64 v[2:3], v[2:3], 0, s[12:13]
	s_waitcnt vmcnt(28)
	v_mul_f32_e32 v12, v129, v129
	v_mul_f32_e32 v13, v131, v131
	v_fmac_f32_e32 v12, v128, v128
	v_fmac_f32_e32 v13, v130, v130
	v_add_f32_e32 v34, v12, v13
	v_mul_f32_e32 v12, v133, v133
	v_mul_f32_e32 v13, v135, v135
	v_fmac_f32_e32 v12, v132, v132
	v_fmac_f32_e32 v13, v134, v134
	v_add_f32_e32 v12, v12, v13
	v_add_f32_e32 v34, v34, v12
	v_mul_f32_e32 v12, v137, v137
	v_mul_f32_e32 v13, v139, v139
	v_fmac_f32_e32 v12, v136, v136
	v_fmac_f32_e32 v13, v138, v138
	v_add_f32_e32 v12, v12, v13
	v_add_f32_e32 v34, v34, v12
	v_mul_f32_e32 v12, v141, v141
	v_mul_f32_e32 v13, v143, v143
	v_fmac_f32_e32 v12, v140, v140
	v_fmac_f32_e32 v13, v142, v142
	v_add_f32_e32 v12, v12, v13
	v_add_f32_e32 v34, v34, v12
	v_cvt_pk_bf16_f32 v128, v128, v129
	v_cvt_pk_bf16_f32 v129, v130, v131
	v_cvt_pk_bf16_f32 v130, v132, v133
	v_cvt_pk_bf16_f32 v131, v134, v135
	v_cvt_pk_bf16_f32 v132, v136, v137
	v_cvt_pk_bf16_f32 v133, v138, v139
	v_cvt_pk_bf16_f32 v134, v140, v141
	v_cvt_pk_bf16_f32 v135, v142, v143
	v_lshl_add_u64 v[28:29], v[2:3], 0, s[50:51]
	global_store_dwordx2 v[28:29], v[128:129], off
	global_store_dwordx2 v[28:29], v[130:131], off offset:512
	global_store_dwordx2 v[28:29], v[132:133], off offset:1024
	global_store_dwordx2 v[28:29], v[134:135], off offset:1536
	v_lshl_add_u64 v[2:3], v[2:3], 0, s[12:13]
	s_waitcnt vmcnt(28)
	v_mul_f32_e32 v12, v145, v145
	v_mul_f32_e32 v13, v147, v147
	v_fmac_f32_e32 v12, v144, v144
	v_fmac_f32_e32 v13, v146, v146
	v_add_f32_e32 v35, v12, v13
	v_mul_f32_e32 v12, v149, v149
	v_mul_f32_e32 v13, v151, v151
	v_fmac_f32_e32 v12, v148, v148
	v_fmac_f32_e32 v13, v150, v150
	v_add_f32_e32 v12, v12, v13
	v_add_f32_e32 v35, v35, v12
	v_mul_f32_e32 v12, v153, v153
	v_mul_f32_e32 v13, v155, v155
	v_fmac_f32_e32 v12, v152, v152
	v_fmac_f32_e32 v13, v154, v154
	v_add_f32_e32 v12, v12, v13
	v_add_f32_e32 v35, v35, v12
	v_mul_f32_e32 v12, v157, v157
	v_mul_f32_e32 v13, v159, v159
	v_fmac_f32_e32 v12, v156, v156
	v_fmac_f32_e32 v13, v158, v158
	v_add_f32_e32 v12, v12, v13
	v_add_f32_e32 v35, v35, v12
	v_cvt_pk_bf16_f32 v144, v144, v145
	v_cvt_pk_bf16_f32 v145, v146, v147
	v_cvt_pk_bf16_f32 v146, v148, v149
	v_cvt_pk_bf16_f32 v147, v150, v151
	v_cvt_pk_bf16_f32 v148, v152, v153
	v_cvt_pk_bf16_f32 v149, v154, v155
	v_cvt_pk_bf16_f32 v150, v156, v157
	v_cvt_pk_bf16_f32 v151, v158, v159
	v_lshl_add_u64 v[28:29], v[2:3], 0, s[50:51]
	global_store_dwordx2 v[28:29], v[144:145], off
	global_store_dwordx2 v[28:29], v[146:147], off offset:512
	global_store_dwordx2 v[28:29], v[148:149], off offset:1024
	global_store_dwordx2 v[28:29], v[150:151], off offset:1536
	v_lshl_add_u64 v[2:3], v[2:3], 0, s[12:13]
	s_waitcnt vmcnt(28)
	v_mul_f32_e32 v12, v161, v161
	v_mul_f32_e32 v13, v163, v163
	v_fmac_f32_e32 v12, v160, v160
	v_fmac_f32_e32 v13, v162, v162
	v_add_f32_e32 v36, v12, v13
	v_mul_f32_e32 v12, v165, v165
	v_mul_f32_e32 v13, v167, v167
	v_fmac_f32_e32 v12, v164, v164
	v_fmac_f32_e32 v13, v166, v166
	v_add_f32_e32 v12, v12, v13
	v_add_f32_e32 v36, v36, v12
	v_mul_f32_e32 v12, v169, v169
	v_mul_f32_e32 v13, v171, v171
	v_fmac_f32_e32 v12, v168, v168
	v_fmac_f32_e32 v13, v170, v170
	v_add_f32_e32 v12, v12, v13
	v_add_f32_e32 v36, v36, v12
	v_mul_f32_e32 v12, v173, v173
	v_mul_f32_e32 v13, v175, v175
	v_fmac_f32_e32 v12, v172, v172
	v_fmac_f32_e32 v13, v174, v174
	v_add_f32_e32 v12, v12, v13
	v_add_f32_e32 v36, v36, v12
	v_cvt_pk_bf16_f32 v160, v160, v161
	v_cvt_pk_bf16_f32 v161, v162, v163
	v_cvt_pk_bf16_f32 v162, v164, v165
	v_cvt_pk_bf16_f32 v163, v166, v167
	v_cvt_pk_bf16_f32 v164, v168, v169
	v_cvt_pk_bf16_f32 v165, v170, v171
	v_cvt_pk_bf16_f32 v166, v172, v173
	v_cvt_pk_bf16_f32 v167, v174, v175
	v_lshl_add_u64 v[28:29], v[2:3], 0, s[50:51]
	global_store_dwordx2 v[28:29], v[160:161], off
	global_store_dwordx2 v[28:29], v[162:163], off offset:512
	global_store_dwordx2 v[28:29], v[164:165], off offset:1024
	global_store_dwordx2 v[28:29], v[166:167], off offset:1536
	v_lshl_add_u64 v[2:3], v[2:3], 0, s[12:13]
	s_waitcnt vmcnt(28)
	v_mul_f32_e32 v12, v177, v177
	v_mul_f32_e32 v13, v179, v179
	v_fmac_f32_e32 v12, v176, v176
	v_fmac_f32_e32 v13, v178, v178
	v_add_f32_e32 v37, v12, v13
	v_mul_f32_e32 v12, v181, v181
	v_mul_f32_e32 v13, v183, v183
	v_fmac_f32_e32 v12, v180, v180
	v_fmac_f32_e32 v13, v182, v182
	v_add_f32_e32 v12, v12, v13
	v_add_f32_e32 v37, v37, v12
	v_mul_f32_e32 v12, v185, v185
	v_mul_f32_e32 v13, v187, v187
	v_fmac_f32_e32 v12, v184, v184
	v_fmac_f32_e32 v13, v186, v186
	v_add_f32_e32 v12, v12, v13
	v_add_f32_e32 v37, v37, v12
	v_mul_f32_e32 v12, v189, v189
	v_mul_f32_e32 v13, v191, v191
	v_fmac_f32_e32 v12, v188, v188
	v_fmac_f32_e32 v13, v190, v190
	v_add_f32_e32 v12, v12, v13
	v_add_f32_e32 v37, v37, v12
	v_cvt_pk_bf16_f32 v176, v176, v177
	v_cvt_pk_bf16_f32 v177, v178, v179
	v_cvt_pk_bf16_f32 v178, v180, v181
	v_cvt_pk_bf16_f32 v179, v182, v183
	v_cvt_pk_bf16_f32 v180, v184, v185
	v_cvt_pk_bf16_f32 v181, v186, v187
	v_cvt_pk_bf16_f32 v182, v188, v189
	v_cvt_pk_bf16_f32 v183, v190, v191
	v_lshl_add_u64 v[28:29], v[2:3], 0, s[50:51]
	global_store_dwordx2 v[28:29], v[176:177], off
	global_store_dwordx2 v[28:29], v[178:179], off offset:512
	global_store_dwordx2 v[28:29], v[180:181], off offset:1024
	global_store_dwordx2 v[28:29], v[182:183], off offset:1536
	v_lshl_add_u64 v[2:3], v[2:3], 0, s[12:13]
	ds_bpermute_b32 v38, v6, v30
	ds_bpermute_b32 v39, v6, v31
	ds_bpermute_b32 v40, v6, v32
	ds_bpermute_b32 v41, v6, v33
	ds_bpermute_b32 v42, v6, v34
	ds_bpermute_b32 v43, v6, v35
	ds_bpermute_b32 v44, v6, v36
	ds_bpermute_b32 v45, v6, v37
	s_waitcnt lgkmcnt(7)
	v_add_f32_e32 v30, v30, v38
	s_waitcnt lgkmcnt(6)
	v_add_f32_e32 v31, v31, v39
	s_waitcnt lgkmcnt(5)
	v_add_f32_e32 v32, v32, v40
	s_waitcnt lgkmcnt(4)
	v_add_f32_e32 v33, v33, v41
	s_waitcnt lgkmcnt(3)
	v_add_f32_e32 v34, v34, v42
	s_waitcnt lgkmcnt(2)
	v_add_f32_e32 v35, v35, v43
	s_waitcnt lgkmcnt(1)
	v_add_f32_e32 v36, v36, v44
	s_waitcnt lgkmcnt(0)
	v_add_f32_e32 v37, v37, v45
	ds_bpermute_b32 v38, v7, v30
	ds_bpermute_b32 v39, v7, v31
	ds_bpermute_b32 v40, v7, v32
	ds_bpermute_b32 v41, v7, v33
	ds_bpermute_b32 v42, v7, v34
	ds_bpermute_b32 v43, v7, v35
	ds_bpermute_b32 v44, v7, v36
	ds_bpermute_b32 v45, v7, v37
	s_waitcnt lgkmcnt(7)
	v_add_f32_e32 v30, v30, v38
	s_waitcnt lgkmcnt(6)
	v_add_f32_e32 v31, v31, v39
	s_waitcnt lgkmcnt(5)
	v_add_f32_e32 v32, v32, v40
	s_waitcnt lgkmcnt(4)
	v_add_f32_e32 v33, v33, v41
	s_waitcnt lgkmcnt(3)
	v_add_f32_e32 v34, v34, v42
	s_waitcnt lgkmcnt(2)
	v_add_f32_e32 v35, v35, v43
	s_waitcnt lgkmcnt(1)
	v_add_f32_e32 v36, v36, v44
	s_waitcnt lgkmcnt(0)
	v_add_f32_e32 v37, v37, v45
	ds_bpermute_b32 v38, v8, v30
	ds_bpermute_b32 v39, v8, v31
	ds_bpermute_b32 v40, v8, v32
	ds_bpermute_b32 v41, v8, v33
	ds_bpermute_b32 v42, v8, v34
	ds_bpermute_b32 v43, v8, v35
	ds_bpermute_b32 v44, v8, v36
	ds_bpermute_b32 v45, v8, v37
	s_waitcnt lgkmcnt(7)
	v_add_f32_e32 v30, v30, v38
	s_waitcnt lgkmcnt(6)
	v_add_f32_e32 v31, v31, v39
	s_waitcnt lgkmcnt(5)
	v_add_f32_e32 v32, v32, v40
	s_waitcnt lgkmcnt(4)
	v_add_f32_e32 v33, v33, v41
	s_waitcnt lgkmcnt(3)
	v_add_f32_e32 v34, v34, v42
	s_waitcnt lgkmcnt(2)
	v_add_f32_e32 v35, v35, v43
	s_waitcnt lgkmcnt(1)
	v_add_f32_e32 v36, v36, v44
	s_waitcnt lgkmcnt(0)
	v_add_f32_e32 v37, v37, v45
	ds_bpermute_b32 v38, v9, v30
	ds_bpermute_b32 v39, v9, v31
	ds_bpermute_b32 v40, v9, v32
	ds_bpermute_b32 v41, v9, v33
	ds_bpermute_b32 v42, v9, v34
	ds_bpermute_b32 v43, v9, v35
	ds_bpermute_b32 v44, v9, v36
	ds_bpermute_b32 v45, v9, v37
	s_waitcnt lgkmcnt(7)
	v_add_f32_e32 v30, v30, v38
	s_waitcnt lgkmcnt(6)
	v_add_f32_e32 v31, v31, v39
	s_waitcnt lgkmcnt(5)
	v_add_f32_e32 v32, v32, v40
	s_waitcnt lgkmcnt(4)
	v_add_f32_e32 v33, v33, v41
	s_waitcnt lgkmcnt(3)
	v_add_f32_e32 v34, v34, v42
	s_waitcnt lgkmcnt(2)
	v_add_f32_e32 v35, v35, v43
	s_waitcnt lgkmcnt(1)
	v_add_f32_e32 v36, v36, v44
	s_waitcnt lgkmcnt(0)
	v_add_f32_e32 v37, v37, v45
	ds_bpermute_b32 v38, v10, v30
	ds_bpermute_b32 v39, v10, v31
	ds_bpermute_b32 v40, v10, v32
	ds_bpermute_b32 v41, v10, v33
	ds_bpermute_b32 v42, v10, v34
	ds_bpermute_b32 v43, v10, v35
	ds_bpermute_b32 v44, v10, v36
	ds_bpermute_b32 v45, v10, v37
	s_waitcnt lgkmcnt(7)
	v_add_f32_e32 v30, v30, v38
	s_waitcnt lgkmcnt(6)
	v_add_f32_e32 v31, v31, v39
	s_waitcnt lgkmcnt(5)
	v_add_f32_e32 v32, v32, v40
	s_waitcnt lgkmcnt(4)
	v_add_f32_e32 v33, v33, v41
	s_waitcnt lgkmcnt(3)
	v_add_f32_e32 v34, v34, v42
	s_waitcnt lgkmcnt(2)
	v_add_f32_e32 v35, v35, v43
	s_waitcnt lgkmcnt(1)
	v_add_f32_e32 v36, v36, v44
	s_waitcnt lgkmcnt(0)
	v_add_f32_e32 v37, v37, v45
	ds_bpermute_b32 v38, v11, v30
	ds_bpermute_b32 v39, v11, v31
	ds_bpermute_b32 v40, v11, v32
	ds_bpermute_b32 v41, v11, v33
	ds_bpermute_b32 v42, v11, v34
	ds_bpermute_b32 v43, v11, v35
	ds_bpermute_b32 v44, v11, v36
	ds_bpermute_b32 v45, v11, v37
	s_waitcnt lgkmcnt(7)
	v_add_f32_e32 v30, v30, v38
	s_waitcnt lgkmcnt(6)
	v_add_f32_e32 v31, v31, v39
	s_waitcnt lgkmcnt(5)
	v_add_f32_e32 v32, v32, v40
	s_waitcnt lgkmcnt(4)
	v_add_f32_e32 v33, v33, v41
	s_waitcnt lgkmcnt(3)
	v_add_f32_e32 v34, v34, v42
	s_waitcnt lgkmcnt(2)
	v_add_f32_e32 v35, v35, v43
	s_waitcnt lgkmcnt(1)
	v_add_f32_e32 v36, v36, v44
	s_waitcnt lgkmcnt(0)
	v_add_f32_e32 v37, v37, v45
	v_lshl_add_u64 v[46:47], s[42:43], 0, v[0:1]
	v_cndmask_b32_e64 v38, 0, v30, s[4:5]
	v_lshl_add_u64 v[0:1], v[0:1], 0, s[10:11]
	v_lshl_add_u64 v[48:49], s[42:43], 0, v[0:1]
	v_cndmask_b32_e64 v39, 0, v31, s[4:5]
	v_lshl_add_u64 v[0:1], v[0:1], 0, s[10:11]
	v_lshl_add_u64 v[50:51], s[42:43], 0, v[0:1]
	v_cndmask_b32_e64 v40, 0, v32, s[4:5]
	v_lshl_add_u64 v[0:1], v[0:1], 0, s[10:11]
	v_lshl_add_u64 v[52:53], s[42:43], 0, v[0:1]
	v_cndmask_b32_e64 v41, 0, v33, s[4:5]
	v_lshl_add_u64 v[0:1], v[0:1], 0, s[10:11]
	v_lshl_add_u64 v[54:55], s[42:43], 0, v[0:1]
	v_cndmask_b32_e64 v42, 0, v34, s[4:5]
	v_lshl_add_u64 v[0:1], v[0:1], 0, s[10:11]
	v_lshl_add_u64 v[56:57], s[42:43], 0, v[0:1]
	v_cndmask_b32_e64 v43, 0, v35, s[4:5]
	v_lshl_add_u64 v[0:1], v[0:1], 0, s[10:11]
	v_lshl_add_u64 v[58:59], s[42:43], 0, v[0:1]
	v_cndmask_b32_e64 v44, 0, v36, s[4:5]
	v_lshl_add_u64 v[0:1], v[0:1], 0, s[10:11]
	v_lshl_add_u64 v[60:61], s[42:43], 0, v[0:1]
	v_cndmask_b32_e64 v45, 0, v37, s[4:5]
	v_lshl_add_u64 v[0:1], v[0:1], 0, s[10:11]
	s_and_saveexec_b64 s[16:17], s[6:7]
	global_store_dword v[46:47], v38, off
	global_store_dword v[48:49], v39, off
	global_store_dword v[50:51], v40, off
	global_store_dword v[52:53], v41, off
	global_store_dword v[54:55], v42, off
	global_store_dword v[56:57], v43, off
	global_store_dword v[58:59], v44, off
	global_store_dword v[60:61], v45, off
	s_or_b64 exec, exec, s[16:17]
	s_lshl_b32 s16, s46, 3
	s_add_i32 s19, s19, s16
	s_cmpk_gt_i32 s19, 0x3fff
	s_cbranch_scc1 .LBB0_49
	s_branch .Lxc_head
	s_branch .LBB0_47

.LBB0_51:
	s_ashr_i32 s7, s6, 31
	s_lshr_b32 s4, s7, 22
	s_add_i32 s4, s6, s4
	s_and_b32 s4, s4, 0xfffffc00
	s_sub_i32 s12, s6, s4
	s_ashr_i32 s13, s12, 31
	s_lshl_b64 s[12:13], s[12:13], 12
	v_lshl_add_u64 v[26:27], v[0:1], 0, s[12:13]
	global_load_dwordx4 v[14:17], v[26:27], off
	global_load_dwordx4 v[18:21], v[26:27], off offset:1024
	global_load_dwordx4 v[22:25], v[26:27], off offset:3072
	s_nop 0
	global_load_dwordx4 v[26:29], v[26:27], off offset:2048
	s_ashr_i32 s5, s4, 31
	v_lshl_add_u64 v[34:35], s[4:5], 2, v[2:3]
	global_load_dwordx4 v[30:33], v[34:35], off
	global_load_dwordx4 v[54:57], v[34:35], off offset:1024
	global_load_dwordx4 v[58:61], v[34:35], off offset:2048
	global_load_dwordx4 v[62:65], v[34:35], off offset:3072
	s_lshl_b64 s[12:13], s[6:7], 11
	s_add_i32 s6, s6, s46
	s_cmpk_lt_i32 s6, 0x800
	s_waitcnt vmcnt(7)
	v_pk_mul_f32 v[36:37], v[16:17], v[16:17]
	v_pk_mul_f32 v[38:39], v[14:15], v[14:15]
	s_waitcnt vmcnt(6)
	v_pk_mul_f32 v[40:41], v[20:21], v[20:21]
	v_pk_mul_f32 v[42:43], v[18:19], v[18:19]
	v_pk_mov_b32 v[48:49], v[38:39], v[36:37] op_sel:[1,0]
	v_mov_b32_e32 v39, v37
	v_pk_mov_b32 v[36:37], v[42:43], v[40:41] op_sel:[1,0]
	v_mov_b32_e32 v43, v41
	s_waitcnt vmcnt(5)
	v_mul_f32_e32 v47, v22, v22
	s_waitcnt vmcnt(4)
	v_mul_f32_e32 v44, v27, v27
	v_mul_f32_e32 v46, v29, v29
	v_pk_add_f32 v[38:39], v[48:49], v[38:39]
	v_pk_add_f32 v[36:37], v[36:37], v[42:43]
	v_mul_f32_e32 v50, v23, v23
	v_mul_f32_e32 v51, v24, v24
	v_mul_f32_e32 v52, v25, v25
	v_pk_fma_f32 v[40:41], v[26:27], v[26:27], v[44:45] op_sel_hi:[1,1,0]
	v_pk_fma_f32 v[44:45], v[28:29], v[28:29], v[46:47] op_sel_hi:[1,1,0]
	v_pk_add_f32 v[38:39], v[38:39], v[38:39] op_sel:[0,1] op_sel_hi:[1,0]
	v_pk_add_f32 v[36:37], v[36:37], v[36:37] op_sel:[0,1] op_sel_hi:[1,0]
	v_mov_b32_e32 v41, v51
	v_mov_b32_e32 v45, v52
	v_mov_b32_e32 v39, v47
	v_mov_b32_e32 v37, v50
	v_pk_add_f32 v[40:41], v[40:41], v[44:45]
	v_pk_add_f32 v[36:37], v[38:39], v[36:37]
	s_nop 0
	v_pk_add_f32 v[36:37], v[36:37], v[40:41]
	s_nop 0
	v_add_f32_e32 v36, v36, v37
	ds_bpermute_b32 v37, v6, v36
	s_waitcnt lgkmcnt(0)
	v_add_f32_e32 v36, v36, v37
	ds_bpermute_b32 v37, v7, v36
	s_waitcnt lgkmcnt(0)
	v_add_f32_e32 v36, v36, v37
	ds_bpermute_b32 v37, v8, v36
	s_waitcnt lgkmcnt(0)
	v_add_f32_e32 v36, v36, v37
	ds_bpermute_b32 v37, v9, v36
	s_waitcnt lgkmcnt(0)
	v_add_f32_e32 v36, v36, v37
	ds_bpermute_b32 v37, v10, v36
	s_waitcnt lgkmcnt(0)
	v_add_f32_e32 v36, v36, v37
	ds_bpermute_b32 v37, v11, v36
	s_waitcnt lgkmcnt(0)
	v_add_f32_e32 v36, v36, v37
	v_fmamk_f32 v36, v36, 0x3a800000, v12
	v_mul_f32_e32 v37, 0x4f800000, v36
	v_cmp_gt_f32_e32 vcc, s10, v36
	s_nop 1
	v_cndmask_b32_e32 v36, v36, v37, vcc
	v_sqrt_f32_e32 v37, v36
	s_nop 0
	v_add_u32_e32 v38, -1, v37
	v_add_u32_e32 v39, 1, v37
	v_fma_f32 v40, -v38, v37, v36
	v_fma_f32 v41, -v39, v37, v36
	v_cmp_ge_f32_e64 s[4:5], 0, v40
	s_nop 1
	v_cndmask_b32_e64 v37, v37, v38, s[4:5]
	v_cmp_lt_f32_e64 s[4:5], 0, v41
	s_nop 1
	v_cndmask_b32_e64 v37, v37, v39, s[4:5]
	v_mul_f32_e32 v38, 0x37800000, v37
	v_cndmask_b32_e32 v37, v37, v38, vcc
	v_cmp_class_f32_e32 vcc, v36, v13
	s_nop 1
	v_cndmask_b32_e32 v38, v37, v36, vcc
	v_div_scale_f32 v39, s[4:5], v38, v38, 1.0
	v_rcp_f32_e32 v40, v39
	v_div_scale_f32 v41, vcc, 1.0, v38, 1.0
	v_lshl_add_u64 v[36:37], v[4:5], 0, s[12:13]
	v_fma_f32 v42, -v39, v40, 1.0
	v_fmac_f32_e32 v40, v42, v40
	v_mul_f32_e32 v42, v41, v40
	v_fma_f32 v43, -v39, v42, v41
	v_fmac_f32_e32 v42, v43, v40
	v_fma_f32 v39, -v39, v42, v41
	v_div_fmas_f32 v39, v39, v40, v42
	v_div_fixup_f32 v38, v39, v38, 1.0
	v_pk_mul_f32 v[14:15], v[14:15], v[38:39] op_sel_hi:[1,0]
	v_pk_mul_f32 v[16:17], v[16:17], v[38:39] op_sel_hi:[1,0]
	s_waitcnt vmcnt(3)
	v_pk_mul_f32 v[14:15], v[30:31], v[14:15]
	v_pk_mul_f32 v[16:17], v[32:33], v[16:17]
	v_cvt_pk_bf16_f32 v14, v14, v15
	v_cvt_pk_bf16_f32 v15, v16, v17
	global_store_dwordx2 v[36:37], v[14:15], off
	s_nop 0
	v_pk_mul_f32 v[18:19], v[18:19], v[38:39] op_sel_hi:[1,0]
	v_pk_mul_f32 v[20:21], v[20:21], v[38:39] op_sel_hi:[1,0]
	s_waitcnt vmcnt(3)
	v_pk_mul_f32 v[14:15], v[54:55], v[18:19]
	v_pk_mul_f32 v[16:17], v[56:57], v[20:21]
	v_cvt_pk_bf16_f32 v14, v14, v15
	v_cvt_pk_bf16_f32 v15, v16, v17
	global_store_dwordx2 v[36:37], v[14:15], off offset:512
	s_nop 0
	v_pk_mul_f32 v[18:19], v[26:27], v[38:39] op_sel_hi:[1,0]
	v_pk_mul_f32 v[20:21], v[28:29], v[38:39] op_sel_hi:[1,0]
	s_waitcnt vmcnt(3)
	v_pk_mul_f32 v[14:15], v[58:59], v[18:19]
	v_pk_mul_f32 v[16:17], v[60:61], v[20:21]
	v_cvt_pk_bf16_f32 v14, v14, v15
	v_cvt_pk_bf16_f32 v15, v16, v17
	global_store_dwordx2 v[36:37], v[14:15], off offset:1024
	s_nop 0
	v_pk_mul_f32 v[18:19], v[22:23], v[38:39] op_sel_hi:[1,0]
	v_pk_mul_f32 v[20:21], v[24:25], v[38:39] op_sel_hi:[1,0]
	s_waitcnt vmcnt(3)
	v_pk_mul_f32 v[14:15], v[62:63], v[18:19]
	v_pk_mul_f32 v[16:17], v[64:65], v[20:21]
	v_cvt_pk_bf16_f32 v14, v14, v15
	v_cvt_pk_bf16_f32 v15, v16, v17
	global_store_dwordx2 v[36:37], v[14:15], off offset:1536
	s_cbranch_scc1 .LBB0_51
